# E26: MLA row-sum via one masked v_mfma_scale_f32_16x16x128 fp8 (8-pass) instead of 32x32x64 ones MFMA (16-pass); same fp8 P values, f32 accumulate
# speedup vs baseline: 1.1196x; 1.0046x over previous
; #define ISSUE_K(j) do { const int _t = (j) < NT ? (j) : NT - 1; char* _d = K_lds + ((j) & 3) * SHM_K8; if (wid < 6) GLDS(K8 + (size_t)_t * 6144 + t16u, _d + tid16); \
;     if (wid < 3) GLDS(Kp8 + (size_t)_t * 3072 + t16u, _d + 6144 + tid16); } while (0)
; #define ISSUE_V(j) do { const int _t = (j) < NT ? (j) : NT - 1; GLDS(V8 + (size_t)_t * 8192 + t16u, V_lds + ((j) & 3) * SHM_V8 + tid16); } while (0)
; #define TILE_SYNC() do { asm volatile("s_waitcnt vmcnt(0)" ::: "memory"); __syncthreads(); } while (0)
; DEVINL void mla_block(const Params& p, const bf16_t* __restrict__ Qn, const bf16_t* __restrict__ Qr, const char* __restrict__ K8, const char* __restrict__ Kp8,
;                       const char* __restrict__ V8, const bf16_t* __restrict__ Gb, bf16_t* __restrict__ Yb, char* lds, int pos0) {
;     ...
;   const int tid16 = tid * 16;
;   const unsigned t16u = (unsigned)tid16;
;     ...
;   f32x16 pA0, pA1, pB0, pB1; float mnA, mnB, alA, alB; i32x8 pa; VFrag vf; constexpr int NT = NT_MLA;
;   const i32x8 ones8 = {0x38383838, 0x38383838, 0x38383838, 0x38383838, 0x38383838, 0x38383838, 0x38383838, 0x38383838};
;   f32x16 lsum;
;     ...
;   ISSUE_K(0); ISSUE_K(1); ISSUE_K(2); ISSUE_V(0); ISSUE_V(1); TILE_SYNC();
.LBB0_559:
	s_or_b64 exec, exec, s[8:9]
	s_mul_i32 s8, s75, 0x208000
	s_add_u32 s14, s58, s8
	v_add_u32_e32 v0, 0x9000, v172
	s_addc_u32 s15, s59, 0
	v_readfirstlane_b32 s9, v0
	v_add_u32_e32 v2, 0xb000, v172
	v_lshl_add_u64 v[140:141], s[14:15], 0, v[138:139]
	s_mov_b32 m0, s9
	v_readfirstlane_b32 s9, v2
	global_load_lds_dwordx4 v[140:141], off
	v_lshl_add_u64 v[0:1], v[140:141], 0, s[48:49]
	s_mov_b32 m0, s9
	v_lshlrev_b32_e32 v170, 9, v48
	global_load_lds_dwordx4 v[0:1], off
	v_and_b32_e32 v0, 0x3fffffc0, v166
	v_lshl_add_u32 v171, v0, 2, s68
	v_add_u32_e32 v0, 0, v170
	v_lshlrev_b32_e32 v176, 3, v167
	v_lshlrev_b32_e32 v175, 4, v167
	v_add_u32_e32 v49, v0, v176
	v_add3_u32 v173, v0, v170, v175
	v_add_u32_e32 v0, 0x1000, v49
	s_waitcnt vmcnt(0)
	s_waitcnt vmcnt(0) lgkmcnt(0)
	s_barrier
; DEVINL void partialSM(f32x16& p0, f32x16& p1, float& m_reg, float& mn, float& alpha, int kvalid, int hi) {
;   constexpr float C = MLA_SCALE * 1.4426950408889634f;
;   if (kvalid < 64) {
; #pragma unroll
;     for (int r = 0; r < 16; ++r) { if (crow(r, hi) >= kvalid) p0[r] = -1e30f; if (32 + crow(r, hi) >= kvalid) p1[r] = -1e30f; }
;   }
;   float pmax = p0[0];
; #pragma unroll
;   for (int r = 1; r < 16; ++r) pmax = fmaxf(pmax, p0[r]);
; #pragma unroll
;   for (int r = 0; r < 16; ++r) pmax = fmaxf(pmax, p1[r]);
;   { auto rr = __builtin_amdgcn_permlane32_swap(__float_as_uint(pmax), __float_as_uint(pmax), false, false);
;     pmax = fmaxf(__uint_as_float(rr[0]), __uint_as_float(rr[1])); }
;   if (__builtin_expect(__all(pmax - m_reg <= THR / MLA_SCALE), 1)) { mn = m_reg; alpha = 1.f; }
;   else { mn = fmaxf(m_reg, pmax); alpha = __builtin_amdgcn_exp2f((m_reg - mn) * C); m_reg = mn; }
;   const float mnC = PSHIFT - mn * C;
;   const f32x2 C2 = {C, C}, M2 = {mnC, mnC};
; #pragma unroll
;   for (int r = 0; r < 16; r += 2) { f32x2 v = {p0[r], p0[r + 1]}; v = __builtin_elementwise_fma(v, C2, M2); p0[r] = v[0]; p0[r + 1] = v[1]; }
; #pragma unroll
;   for (int r = 0; r < 16; r += 2) { f32x2 v = {p1[r], p1[r + 1]}; v = __builtin_elementwise_fma(v, C2, M2); p1[r] = v[0]; p1[r + 1] = v[1]; }
; #pragma unroll
;   for (int r = 0; r < 16; ++r) p0[r] = __builtin_amdgcn_exp2f(p0[r]);
; }
; template <bool FUSE>
; DEVINL void qkt(f32x16& p0, f32x16& p1, const char* Ks, const i32x8* q8, int r32, int hi, f32x16& e1) {
;   p0 = f32x16{}; p1 = f32x16{};
;   const char* ka = Ks + hi * 1024 + r32 * 16; const char* kb = Ks + 4096 + hi * 512 + r32 * 8;
;   const char* ra = Ks + 6144 + hi * 1024 + r32 * 16; const char* rb = Ks + 6144 + 2048 + hi * 512 + r32 * 8;
;   u32x4 fa[3][2]; u32x2 fb[3][2];
;     ...
;   QK_LD(0, 0);
; #pragma unroll
;   for (int t = 0; t < 3; ++t) {
;     if (t + 1 < 3) QK_LD(t + 1, (t + 1) % 3);
;     const i32x8 a0 = mk6((int)fa[t][0][0], (int)fa[t][0][1], (int)fa[t][0][2], (int)fa[t][0][3], (int)fb[t][0][0], (int)fb[t][0][1]);
;     const i32x8 a1 = mk6((int)fa[t][1][0], (int)fa[t][1][1], (int)fa[t][1][2], (int)fa[t][1][3], (int)fb[t][1][0], (int)fb[t][1][1]);
;     p0 = MFMA6(a0, q8[t], p0);
;     if (FUSE) {
; #pragma unroll
;       for (int r = 0; r < 3; ++r) { const int rr = t * 6 + r; if (rr < 16) e1[rr] = __builtin_amdgcn_exp2f(e1[rr]); }
;     }
	ds_read2_b64 v[4:7], v0 offset1:32
	ds_read_b128 v[50:53], v173 offset:2048
	ds_read_b128 v[56:59], v173 offset:2560
	ds_read2_b64 v[60:63], v0 offset0:128 offset1:160
	ds_read_b128 v[16:19], v173 offset:512
	ds_read_b128 v[0:3], v173
	s_waitcnt lgkmcnt(5)
	v_mov_b32_e32 v20, v6
	v_mov_b32_e32 v21, v7
	s_waitcnt lgkmcnt(0)
	v_mfma_scale_f32_32x32x64_f8f6f4 v[32:47], v[0:5], v[120:125], 0, v162, v162 op_sel_hi:[0,0,0] cbsz:2 blgp:2
	s_mov_b32 s12, s13
	s_mov_b32 s14, s13
	s_mov_b32 s15, s13
	s_mov_b32 s16, s13
	s_mov_b32 s17, s13
	s_mov_b32 s18, s13
	s_mov_b32 s19, s13
	v_mfma_scale_f32_32x32x64_f8f6f4 v[16:31], v[16:21], v[120:125], 0, v162, v162 op_sel_hi:[0,0,0] cbsz:2 blgp:2
	s_mov_b32 s20, s13
	s_mov_b32 s21, s13
	s_mov_b32 s22, s13
	s_mov_b32 s23, s13
	s_mov_b32 s24, s13
	s_mov_b32 s25, s13
	s_mov_b32 s26, s13
	s_mov_b32 s27, s13
	v_mov_b64_e32 v[0:1], s[12:13]
	v_and_b32_e32 v169, 63, v166
	v_lshlrev_b32_e32 v174, 10, v48
	s_mov_b32 s53, 4
	v_mov_b64_e32 v[2:3], s[14:15]
	v_mov_b64_e32 v[4:5], s[16:17]
	v_mov_b64_e32 v[6:7], s[18:19]
	v_mov_b64_e32 v[8:9], s[20:21]
	v_mov_b64_e32 v[10:11], s[22:23]
	v_mov_b64_e32 v[12:13], s[24:25]
	v_mov_b64_e32 v[14:15], s[26:27]
	v_mov_b32_e32 v54, v60
	v_mov_b32_e32 v55, v61
	v_mov_b32_e32 v60, v62
	v_mov_b32_e32 v61, v63
	v_add_u32_e32 v49, 0x2000, v49
	v_mfma_scale_f32_32x32x64_f8f6f4 v[32:47], v[50:55], v[126:131], v[32:47], v162, v162 op_sel_hi:[0,0,0] cbsz:2 blgp:2
	ds_read_b128 v[50:53], v173 offset:6144
	ds_read_b128 v[62:65], v173 offset:6656
	ds_read2_b64 v[66:69], v49 offset1:32
	v_mfma_scale_f32_32x32x64_f8f6f4 v[16:31], v[56:61], v[126:131], v[16:31], v162, v162 op_sel_hi:[0,0,0] cbsz:2 blgp:2
	s_waitcnt lgkmcnt(0)
	v_mov_b32_e32 v54, v66
	v_mov_b32_e32 v55, v67
	v_mov_b32_e32 v66, v68
	v_mov_b32_e32 v67, v69
	v_mfma_scale_f32_32x32x64_f8f6f4 v[32:47], v[50:55], v[132:137], v[32:47], v162, v162 op_sel_hi:[0,0,0] cbsz:2 blgp:2
	s_nop 0
	v_mfma_scale_f32_32x32x64_f8f6f4 v[16:31], v[62:67], v[132:137], v[16:31], v162, v162 op_sel_hi:[0,0,0] cbsz:2 blgp:2
	s_nop 9
	v_max_f32_e32 v49, v33, v33
	v_max_f32_e32 v50, v32, v32
	v_max_f32_e32 v49, v50, v49
	v_max3_f32 v49, v49, v34, v35
	v_max3_f32 v49, v49, v36, v37
	v_max3_f32 v49, v49, v38, v39
	v_max3_f32 v49, v49, v40, v41
	v_max3_f32 v49, v49, v42, v43
	v_max3_f32 v49, v49, v44, v45
	v_max3_f32 v49, v49, v46, v47
	v_max3_f32 v49, v49, v16, v17
	v_max3_f32 v49, v49, v18, v19
	v_max3_f32 v49, v49, v20, v21
	v_max3_f32 v49, v49, v22, v23
	v_max3_f32 v49, v49, v24, v25
	v_max3_f32 v49, v49, v26, v27
	v_max3_f32 v49, v49, v28, v29
	v_max3_f32 v49, v49, v30, v31
	v_mov_b32_e32 v50, v49
	s_nop 1
	v_permlane32_swap_b32_e32 v49, v50
	v_max_f32_e32 v50, v50, v50
	v_max_f32_e32 v49, v49, v49
	v_max_f32_e32 v49, v49, v50
	v_add_f32_e32 v50, 0x7149f2ca, v49
	v_max_f32_e32 v49, 0xf149f2ca, v49
	v_sub_f32_e32 v51, 0xf149f2ca, v49
	v_mul_f32_e32 v51, 0x3dd53b94, v51
	v_cmp_ge_f32_e32 vcc, s69, v50
	v_exp_f32_e32 v51, v51
	s_cmp_eq_u64 vcc, exec
	s_cselect_b64 vcc, -1, 0
	v_cndmask_b32_e32 v181, v49, v163, vcc
	v_fmamk_f32 v50, v181, 0xbdd53b94, v164
	v_pk_fma_f32 v[32:33], v[32:33], s[50:51], v[50:51] op_sel_hi:[1,0,0]
	v_pk_fma_f32 v[34:35], v[34:35], s[50:51], v[50:51] op_sel_hi:[1,0,0]
	v_pk_fma_f32 v[36:37], v[36:37], s[50:51], v[50:51] op_sel_hi:[1,0,0]
	v_pk_fma_f32 v[38:39], v[38:39], s[50:51], v[50:51] op_sel_hi:[1,0,0]
	v_pk_fma_f32 v[40:41], v[40:41], s[50:51], v[50:51] op_sel_hi:[1,0,0]
	v_pk_fma_f32 v[42:43], v[42:43], s[50:51], v[50:51] op_sel_hi:[1,0,0]
	v_pk_fma_f32 v[44:45], v[44:45], s[50:51], v[50:51] op_sel_hi:[1,0,0]
	v_pk_fma_f32 v[46:47], v[46:47], s[50:51], v[50:51] op_sel_hi:[1,0,0]
	v_exp_f32_e32 v65, v32
	v_exp_f32_e32 v197, v33
	v_exp_f32_e32 v187, v34
	v_exp_f32_e32 v189, v35
	v_exp_f32_e32 v195, v36
	v_exp_f32_e32 v196, v37
	v_exp_f32_e32 v191, v38
	v_exp_f32_e32 v192, v39
	v_exp_f32_e32 v193, v40
	v_exp_f32_e32 v194, v41
	v_exp_f32_e32 v183, v42
	v_exp_f32_e32 v184, v43
	v_exp_f32_e32 v188, v44
	v_exp_f32_e32 v190, v45
	v_exp_f32_e32 v185, v46
	v_exp_f32_e32 v186, v47
	s_add_u32 s8, s30, s8
	v_cndmask_b32_e64 v179, v51, 1.0, vcc
	v_pk_fma_f32 v[148:149], v[30:31], s[50:51], v[50:51] op_sel_hi:[1,0,0]
	v_pk_fma_f32 v[150:151], v[28:29], s[50:51], v[50:51] op_sel_hi:[1,0,0]
	v_pk_fma_f32 v[152:153], v[26:27], s[50:51], v[50:51] op_sel_hi:[1,0,0]
	v_pk_fma_f32 v[154:155], v[24:25], s[50:51], v[50:51] op_sel_hi:[1,0,0]
	v_pk_fma_f32 v[156:157], v[22:23], s[50:51], v[50:51] op_sel_hi:[1,0,0]
	v_pk_fma_f32 v[82:83], v[20:21], s[50:51], v[50:51] op_sel_hi:[1,0,0]
	v_pk_fma_f32 v[158:159], v[18:19], s[50:51], v[50:51] op_sel_hi:[1,0,0]
	v_pk_fma_f32 v[160:161], v[16:17], s[50:51], v[50:51] op_sel_hi:[1,0,0]
	v_lshlrev_b32_e32 v177, 4, v48
	s_addc_u32 s9, s31, 0
	v_mov_b64_e32 v[62:63], v[14:15]
	v_mov_b64_e32 v[30:31], v[14:15]
	v_mov_b64_e32 v[46:47], v[14:15]
	v_lshl_add_u64 v[142:143], s[6:7], 0, v[138:139]
	v_lshl_add_u64 v[144:145], s[34:35], 0, v[138:139]
	v_cmp_gt_u32_e64 s[6:7], 32, v169
	v_lshl_add_u32 v178, v167, 2, v171
	v_lshl_add_u64 v[146:147], s[8:9], 0, v[138:139]
	v_mov_b32_e32 v180, 0
	s_mov_b64 s[14:15], 0x89dc400
	v_mov_b64_e32 v[60:61], v[12:13]
	v_mov_b64_e32 v[58:59], v[10:11]
	v_mov_b64_e32 v[56:57], v[8:9]
	v_mov_b64_e32 v[54:55], v[6:7]
	v_mov_b64_e32 v[52:53], v[4:5]
	v_mov_b64_e32 v[50:51], v[2:3]
	v_mov_b64_e32 v[48:49], v[0:1]
	v_mov_b64_e32 v[28:29], v[12:13]
	v_mov_b64_e32 v[26:27], v[10:11]
	v_mov_b64_e32 v[24:25], v[8:9]
	v_mov_b64_e32 v[22:23], v[6:7]
	v_mov_b64_e32 v[20:21], v[4:5]
	v_mov_b64_e32 v[18:19], v[2:3]
	v_mov_b64_e32 v[16:17], v[0:1]
	v_mov_b64_e32 v[44:45], v[12:13]
	v_mov_b64_e32 v[42:43], v[10:11]
	v_mov_b64_e32 v[40:41], v[8:9]
	v_mov_b64_e32 v[38:39], v[6:7]
	v_mov_b64_e32 v[36:37], v[4:5]
	v_mov_b64_e32 v[34:35], v[2:3]
	v_mov_b64_e32 v[32:33], v[0:1]
	v_lshrrev_b32_e32 v175, 4, v169
	v_and_b32_e32 v175, 1, v175
	v_bfe_u32 v174, v169, 2, 2
	v_cmp_eq_u32_e64 s[8:9], v174, v175
	s_nop 1
	v_cndmask_b32_e64 v232, 0, v112, s[8:9]
	v_mov_b32_e32 v233, v232
	v_mov_b32_e32 v234, v232
	v_mov_b32_e32 v235, v232
	v_mov_b32_e32 v236, v232
	v_mov_b32_e32 v237, v232
	v_mov_b32_e32 v238, v232
	v_mov_b32_e32 v239, v232
	v_add_u32_e32 v176, v170, v176
	v_add_u32_e32 v176, 0x1000, v176
	v_add_u32_e32 v174, 0x2400, v173
	v_add_u32_e32 v175, 0x2400, v176
	ds_read_b128 v[204:207], v174
	ds_read_b64 v[208:209], v175
	ds_read_b128 v[216:219], v174 offset:512
	ds_read_b64 v[220:221], v175 offset:256
	s_lshl_b32 s78, s3, 4
	s_add_i32 s79, s78, 0x9000
	s_mul_i32 s80, s75, 0x186000
	s_add_u32 s80, s56, s80
	s_addc_u32 s81, s57, 0
	s_mov_b64 s[82:83], s[34:35]
	s_mul_i32 s84, s75, 0x208000
	s_add_u32 s84, s58, s84
	s_addc_u32 s85, s59, 0
	v_lshlrev_b32_e32 v231, 4, v169
	v_mov_b32_e32 v227, v181
	v_fmamk_f32 v230, v181, 0xbdd53b94, v164
	v_add_u32_e32 v140, 0x8000, v173
	s_cmp_ge_u32 s3, 0x100
	s_cbranch_scc1 .Lprio_skip
	s_setprio 2

; DEVINL int crow(int r, int hi) { return (r & 3) + 8 * (r >> 2) + 4 * hi; }
; #define SBAR() __builtin_amdgcn_sched_barrier(0)
; #define MFMA8(A, B, C) __builtin_amdgcn_mfma_scale_f32_32x32x64_f8f6f4(A, B, C, 0, 0, 0, 0x7f7f7f7f, 0, 0x7f7f7f7f)
; #define PVM(db) do { const i32x8 b = {(int)f.v[db][0][0], (int)f.v[db][0][1], (int)f.v[db][0][2], (int)f.v[db][0][3], (int)f.v[db][1][0], (int)f.v[db][1][1], (int)f.v[db][1][2], (int)f.v[db][1][3]}; \
;     o[db] = MFMA8(pa, b, o[db]); } while (0)
; DEVINL void pv_psm(f32x16* o, const VFrag& f, const i32x8& pa, f32x16& lsum, const i32x8& ones8,
;                    f32x16& p0, f32x16& p1, float& m_reg, float& mn, float& alpha, int kvalid, int hi) {
;   constexpr float C = MLA_SCALE * 1.4426950408889634f;
;     ...
;   if (kvalid < 64) {
; #pragma unroll
;     for (int r = 0; r < 16; ++r) { if (crow(r, hi) >= kvalid) p0[r] = -1e30f; if (32 + crow(r, hi) >= kvalid) p1[r] = -1e30f; }
;   }
;   PVM(0);
;   float pmax = p0[0];
; #pragma unroll
;   for (int r = 1; r < 16; ++r) pmax = fmaxf(pmax, p0[r]);
;   SBAR();
;   PVM(1);
; #pragma unroll
;   for (int r = 0; r < 16; ++r) pmax = fmaxf(pmax, p1[r]);
;   { auto rr = __builtin_amdgcn_permlane32_swap(__float_as_uint(pmax), __float_as_uint(pmax), false, false);
;     pmax = fmaxf(__uint_as_float(rr[0]), __uint_as_float(rr[1])); }
;   SBAR();
;   PVM(2);
;   if (__builtin_expect(__all(pmax - m_reg <= THR / MLA_SCALE), 1)) { mn = m_reg; alpha = 1.f; }
;   else { mn = fmaxf(m_reg, pmax); alpha = __builtin_amdgcn_exp2f((m_reg - mn) * C); m_reg = mn; }
;   const float mnC = PSHIFT - mn * C;
;   const f32x2 C2 = {C, C}, M2 = {mnC, mnC};
; #pragma unroll
;   for (int r = 0; r < 16; r += 2) { f32x2 v = {p0[r], p0[r + 1]}; v = __builtin_elementwise_fma(v, C2, M2); p0[r] = v[0]; p0[r + 1] = v[1]; }
;   SBAR();
;   PVM(3);
; #pragma unroll
;   for (int r = 0; r < 16; r += 2) { f32x2 v = {p1[r], p1[r + 1]}; v = __builtin_elementwise_fma(v, C2, M2); p1[r] = v[0]; p1[r + 1] = v[1]; }
; #pragma unroll
;   for (int r = 0; r < 8; ++r) p0[r] = __builtin_amdgcn_exp2f(p0[r]);
;   SBAR();
;   lsum = MFMA8(ones8, pa, (f32x16{}));
; #pragma unroll
;   for (int r = 8; r < 16; ++r) p0[r] = __builtin_amdgcn_exp2f(p0[r]);
;   SBAR();
;     ...
; }
.Ldma_done:
	ds_read_b128 v[114:117], v173 offset:11264
	ds_read_b128 v[198:201], v173 offset:11776
	ds_read_b64 v[118:119], v176 offset:10240
	ds_read_b64 v[202:203], v176 offset:10496
	v_exp_f32_e32 v182, v82
	s_waitcnt lgkmcnt(4)
	v_exp_f32_e32 v214, v83
	v_mfma_scale_f32_32x32x64_f8f6f4 v[96:111], v[204:209], v[120:125], 0, v162, v162 op_sel_hi:[0,0,0] cbsz:2 blgp:2
	v_exp_f32_e32 v160, v160
	v_exp_f32_e32 v161, v161
	v_exp_f32_e32 v158, v158
	v_exp_f32_e32 v159, v159
	v_mfma_scale_f32_32x32x64_f8f6f4 v[80:95], v[216:221], v[120:125], 0, v162, v162 op_sel_hi:[0,0,0] cbsz:2 blgp:2
	ds_read_b128 v[66:69], v173 offset:15360
	ds_read_b128 v[72:75], v173 offset:15872
	ds_read_b64 v[70:71], v176 offset:13312
	ds_read_b64 v[76:77], v176 offset:13568
	s_waitcnt lgkmcnt(4)
	v_mfma_scale_f32_32x32x64_f8f6f4 v[96:111], v[114:119], v[126:131], v[96:111], v162, v162 op_sel_hi:[0,0,0] cbsz:2 blgp:2
	v_exp_f32_e32 v113, v156
	v_exp_f32_e32 v114, v157
	v_exp_f32_e32 v115, v154
	v_exp_f32_e32 v116, v155
	v_exp_f32_e32 v117, v152
	v_mfma_scale_f32_32x32x64_f8f6f4 v[80:95], v[198:203], v[126:131], v[80:95], v162, v162 op_sel_hi:[0,0,0] cbsz:2 blgp:2
	v_exp_f32_e32 v118, v153
	s_waitcnt lgkmcnt(0)
	v_exp_f32_e32 v119, v150
	v_mfma_scale_f32_32x32x64_f8f6f4 v[96:111], v[66:71], v[132:137], v[96:111], v162, v162 op_sel_hi:[0,0,0] cbsz:2 blgp:2
	v_exp_f32_e32 v156, v151
	v_exp_f32_e32 v157, v148
	v_exp_f32_e32 v215, v149
	v_mfma_scale_f32_32x32x64_f8f6f4 v[80:95], v[72:77], v[132:137], v[80:95], v162, v162 op_sel_hi:[0,0,0] cbsz:2 blgp:2
	ds_read_b128 v[72:75], v140 offset:4096
	ds_read_b128 v[76:79], v140 offset:4608
	ds_read_b128 v[148:151], v140 offset:6144
	ds_read_b128 v[152:155], v140 offset:6656
	ds_read_b128 v[198:201], v140 offset:8192
	ds_read_b128 v[202:205], v140 offset:8704
	ds_read_b128 v[206:209], v140 offset:10240
	ds_read_b128 v[210:213], v140 offset:10752
	v_cvt_pk_fp8_f32 v64, v65, v197
	v_cvt_pk_fp8_f32 v68, v160, v161
	v_cvt_pk_fp8_f32 v65, v195, v196
	v_cvt_pk_fp8_f32 v69, v182, v214
	v_cvt_pk_fp8_f32 v66, v193, v194
	v_cvt_pk_fp8_f32 v70, v115, v116
	v_cvt_pk_fp8_f32 v67, v188, v190
	v_cvt_pk_fp8_f32 v71, v119, v156
	v_cvt_pk_fp8_f32 v64, v187, v189 op_sel:[0,0,1]
	v_cvt_pk_fp8_f32 v68, v158, v159 op_sel:[0,0,1]
	v_cvt_pk_fp8_f32 v65, v191, v192 op_sel:[0,0,1]
	v_cvt_pk_fp8_f32 v69, v113, v114 op_sel:[0,0,1]
	v_cvt_pk_fp8_f32 v66, v183, v184 op_sel:[0,0,1]
	v_cvt_pk_fp8_f32 v70, v117, v118 op_sel:[0,0,1]
	v_cvt_pk_fp8_f32 v67, v185, v186 op_sel:[0,0,1]
	v_cvt_pk_fp8_f32 v71, v157, v215 op_sel:[0,0,1]
	s_waitcnt lgkmcnt(0)
	s_nop 0
	v_mfma_scale_f32_32x32x64_f8f6f4 v[0:15], v[64:71], v[72:79], v[0:15], v162, v162 op_sel_hi:[0,0,0]
	v_max_f32_e32 v113, v96, v97
	v_max3_f32 v113, v113, v98, v99
	v_max3_f32 v113, v113, v100, v101
	v_max3_f32 v113, v113, v102, v103
	v_max3_f32 v113, v113, v104, v105
	v_max3_f32 v113, v113, v106, v107
	v_max3_f32 v113, v113, v108, v109
	v_max3_f32 v113, v113, v110, v111
	v_mfma_scale_f32_32x32x64_f8f6f4 v[48:63], v[64:71], v[148:155], v[48:63], v162, v162 op_sel_hi:[0,0,0]
	v_max3_f32 v72, v113, v80, v81
	v_max3_f32 v72, v72, v82, v83
	v_max3_f32 v72, v72, v84, v85
	v_max3_f32 v72, v72, v86, v87
	v_max3_f32 v72, v72, v88, v89
	v_max3_f32 v72, v72, v90, v91
	v_max3_f32 v72, v72, v92, v93
	v_max3_f32 v72, v72, v94, v95
	v_mov_b32_e32 v73, v72
	s_nop 1
	v_permlane32_swap_b32_e32 v72, v73
	v_max_f32_e32 v72, v72, v73
	v_mfma_scale_f32_32x32x64_f8f6f4 v[16:31], v[64:71], v[198:205], v[16:31], v162, v162 op_sel_hi:[0,0,0]
	v_sub_f32_e32 v73, v72, v227
	v_cmp_ge_f32_e32 vcc, s69, v73
	s_cmp_eq_u64 vcc, exec
	s_cselect_b64 s[8:9], -1, 0
	v_mov_b32_e32 v182, 1.0
	v_mfma_scale_f32_32x32x64_f8f6f4 v[32:47], v[64:71], v[206:213], v[32:47], v162, v162 op_sel_hi:[0,0,0]
	v_mfma_scale_f32_16x16x128_f8f6f4 v[240:243], v[232:239], v[64:71], 0, v162, v162 op_sel_hi:[0,0,0]
	ds_read_b128 v[200:203], v173 offset:18432
	ds_read_b64 v[204:205], v176 offset:18432
	ds_read_b128 v[206:209], v173 offset:18944
	ds_read_b64 v[210:211], v176 offset:18688
	s_and_b64 vcc, exec, s[8:9]
	s_cbranch_vccnz .LBB0_572
	v_max_f32_e32 v148, v227, v72
	v_sub_f32_e32 v72, v227, v148
	v_mul_f32_e32 v72, 0x3dd53b94, v72
	v_exp_f32_e32 v182, v72
	v_mov_b32_e32 v227, v148
	v_fmamk_f32 v230, v148, 0xbdd53b94, v164
	s_and_saveexec_b64 s[16:17], s[6:7]
	ds_write_b32 v178, v182 offset:128
	s_or_b64 exec, exec, s[16:17]
	s_waitcnt lgkmcnt(0)
	v_add_u32_e32 v113, v171, v177
	ds_read_b128 v[72:75], v113 offset:224
	ds_read_b128 v[76:79], v113 offset:192
	ds_read_b128 v[114:117], v113 offset:160
	ds_read_b128 v[150:153], v113 offset:128
	s_waitcnt lgkmcnt(0)
	v_pk_mul_f32 v[12:13], v[12:13], v[72:73]
	v_pk_mul_f32 v[8:9], v[8:9], v[76:77]
	v_pk_mul_f32 v[4:5], v[4:5], v[114:115]
	v_pk_mul_f32 v[14:15], v[14:15], v[74:75]
	v_pk_mul_f32 v[10:11], v[10:11], v[78:79]
	v_pk_mul_f32 v[6:7], v[6:7], v[116:117]
	v_pk_mul_f32 v[2:3], v[2:3], v[152:153]
	v_pk_mul_f32 v[0:1], v[0:1], v[150:151]
	v_pk_mul_f32 v[60:61], v[60:61], v[72:73]
	v_pk_mul_f32 v[56:57], v[56:57], v[76:77]
	v_pk_mul_f32 v[52:53], v[52:53], v[114:115]
	v_pk_mul_f32 v[62:63], v[62:63], v[74:75]
	v_pk_mul_f32 v[58:59], v[58:59], v[78:79]
	v_pk_mul_f32 v[54:55], v[54:55], v[116:117]
	v_pk_mul_f32 v[50:51], v[50:51], v[152:153]
	v_pk_mul_f32 v[48:49], v[48:49], v[150:151]
	v_pk_mul_f32 v[28:29], v[28:29], v[72:73]
	v_pk_mul_f32 v[24:25], v[24:25], v[76:77]
	v_pk_mul_f32 v[20:21], v[20:21], v[114:115]
	v_pk_mul_f32 v[30:31], v[30:31], v[74:75]
	v_pk_mul_f32 v[26:27], v[26:27], v[78:79]
	v_pk_mul_f32 v[22:23], v[22:23], v[116:117]
	v_pk_mul_f32 v[18:19], v[18:19], v[152:153]
	v_pk_mul_f32 v[16:17], v[16:17], v[150:151]
	v_pk_mul_f32 v[44:45], v[44:45], v[72:73]
	v_pk_mul_f32 v[40:41], v[40:41], v[76:77]
	v_pk_mul_f32 v[36:37], v[36:37], v[114:115]
	v_pk_mul_f32 v[46:47], v[46:47], v[74:75]
	v_pk_mul_f32 v[42:43], v[42:43], v[78:79]
	v_pk_mul_f32 v[38:39], v[38:39], v[116:117]
	v_pk_mul_f32 v[34:35], v[34:35], v[152:153]
	v_pk_mul_f32 v[32:33], v[32:33], v[150:151]

; #define SBAR() __builtin_amdgcn_sched_barrier(0)
; #define MFMA8(A, B, C) __builtin_amdgcn_mfma_scale_f32_32x32x64_f8f6f4(A, B, C, 0, 0, 0, 0x7f7f7f7f, 0, 0x7f7f7f7f)
; #define PVM(db) do { const i32x8 b = {(int)f.v[db][0][0], (int)f.v[db][0][1], (int)f.v[db][0][2], (int)f.v[db][0][3], (int)f.v[db][1][0], (int)f.v[db][1][1], (int)f.v[db][1][2], (int)f.v[db][1][3]}; \
;     o[db] = MFMA8(pa, b, o[db]); } while (0)
; DEVINL void pv_psm(f32x16* o, const VFrag& f, const i32x8& pa, f32x16& lsum, const i32x8& ones8,
;                    f32x16& p0, f32x16& p1, float& m_reg, float& mn, float& alpha, int kvalid, int hi) {
;     ...
;   const float mnC = PSHIFT - mn * C;
;   const f32x2 C2 = {C, C}, M2 = {mnC, mnC};
; #pragma unroll
;   for (int r = 0; r < 16; r += 2) { f32x2 v = {p0[r], p0[r + 1]}; v = __builtin_elementwise_fma(v, C2, M2); p0[r] = v[0]; p0[r + 1] = v[1]; }
;   SBAR();
;   PVM(3);
; #pragma unroll
;   for (int r = 0; r < 16; r += 2) { f32x2 v = {p1[r], p1[r + 1]}; v = __builtin_elementwise_fma(v, C2, M2); p1[r] = v[0]; p1[r + 1] = v[1]; }
; #pragma unroll
;   for (int r = 0; r < 8; ++r) p0[r] = __builtin_amdgcn_exp2f(p0[r]);
;   SBAR();
;   lsum = MFMA8(ones8, pa, (f32x16{}));
; #pragma unroll
;   for (int r = 8; r < 16; ++r) p0[r] = __builtin_amdgcn_exp2f(p0[r]);
;   SBAR();
;     ...
; }
.LBB0_576:
	ds_read_b128 v[204:207], v173 offset:27648
	ds_read_b64 v[208:209], v176 offset:27648
	ds_read_b128 v[216:219], v173 offset:28160
	ds_read_b64 v[220:221], v176 offset:27904
	v_pk_fma_f32 v[228:229], v[74:75], s[50:51], v[230:231] op_sel_hi:[1,0,0]
	v_pk_fma_f32 v[66:67], v[66:67], s[50:51], v[230:231] op_sel_hi:[1,0,0]
	v_pk_fma_f32 v[68:69], v[68:69], s[50:51], v[230:231] op_sel_hi:[1,0,0]
	v_pk_fma_f32 v[70:71], v[70:71], s[50:51], v[230:231] op_sel_hi:[1,0,0]
	v_pk_fma_f32 v[72:73], v[72:73], s[50:51], v[230:231] op_sel_hi:[1,0,0]
	v_pk_fma_f32 v[154:155], v[90:91], s[50:51], v[230:231] op_sel_hi:[1,0,0]
	v_pk_fma_f32 v[152:153], v[92:93], s[50:51], v[230:231] op_sel_hi:[1,0,0]
	v_pk_fma_f32 v[150:151], v[94:95], s[50:51], v[230:231] op_sel_hi:[1,0,0]
	v_pk_fma_f32 v[148:149], v[96:97], s[50:51], v[230:231] op_sel_hi:[1,0,0]
	v_exp_f32_e32 v65, v66
	v_exp_f32_e32 v197, v67
	v_exp_f32_e32 v187, v68
	v_exp_f32_e32 v189, v69
	v_exp_f32_e32 v195, v70
	v_exp_f32_e32 v196, v71
	v_exp_f32_e32 v191, v72
	v_exp_f32_e32 v192, v73
	v_fma_f32 v180, v179, v180, v240
	v_mfma_scale_f32_16x16x128_f8f6f4 v[240:243], v[232:239], v[98:105], 0, v162, v162 op_sel_hi:[0,0,0]
	v_fma_f32 v94, v76, s50, v230
	v_fma_f32 v95, v77, s50, v230
	v_fma_f32 v96, v78, s50, v230
	v_fma_f32 v97, v79, s50, v230
	v_fma_f32 v106, v80, s50, v230
	v_fma_f32 v107, v81, s50, v230
	v_exp_f32_e32 v193, v228
	v_exp_f32_e32 v194, v229
	v_exp_f32_e32 v183, v94
	v_exp_f32_e32 v184, v95
	v_exp_f32_e32 v188, v96
	v_exp_f32_e32 v190, v97
	v_exp_f32_e32 v185, v106
	v_exp_f32_e32 v186, v107
	s_add_i32 s53, s53, 2
	v_pk_fma_f32 v[160:161], v[82:83], s[50:51], v[230:231] op_sel_hi:[1,0,0]
	v_pk_fma_f32 v[158:159], v[84:85], s[50:51], v[230:231] op_sel_hi:[1,0,0]
	v_pk_fma_f32 v[82:83], v[86:87], s[50:51], v[230:231] op_sel_hi:[1,0,0]
	v_pk_fma_f32 v[156:157], v[88:89], s[50:51], v[230:231] op_sel_hi:[1,0,0]
	s_nop 1
	v_fma_f32 v180, v182, v180, v240
	v_mov_b32_e32 v179, v198

; DEVINL int crow(int r, int hi) { return (r & 3) + 8 * (r >> 2) + 4 * hi; }
; #define SBAR() __builtin_amdgcn_sched_barrier(0)
; #define MFMA8(A, B, C) __builtin_amdgcn_mfma_scale_f32_32x32x64_f8f6f4(A, B, C, 0, 0, 0, 0x7f7f7f7f, 0, 0x7f7f7f7f)
; #define PVM(db) do { const i32x8 b = {(int)f.v[db][0][0], (int)f.v[db][0][1], (int)f.v[db][0][2], (int)f.v[db][0][3], (int)f.v[db][1][0], (int)f.v[db][1][1], (int)f.v[db][1][2], (int)f.v[db][1][3]}; \
;     o[db] = MFMA8(pa, b, o[db]); } while (0)
; DEVINL void pv_psm(f32x16* o, const VFrag& f, const i32x8& pa, f32x16& lsum, const i32x8& ones8,
;                    f32x16& p0, f32x16& p1, float& m_reg, float& mn, float& alpha, int kvalid, int hi) {
;   constexpr float C = MLA_SCALE * 1.4426950408889634f;
;     ...
;   if (kvalid < 64) {
; #pragma unroll
;     for (int r = 0; r < 16; ++r) { if (crow(r, hi) >= kvalid) p0[r] = -1e30f; if (32 + crow(r, hi) >= kvalid) p1[r] = -1e30f; }
;   }
;   PVM(0);
;   float pmax = p0[0];
; #pragma unroll
;   for (int r = 1; r < 16; ++r) pmax = fmaxf(pmax, p0[r]);
;   SBAR();
;   PVM(1);
; #pragma unroll
;   for (int r = 0; r < 16; ++r) pmax = fmaxf(pmax, p1[r]);
;   { auto rr = __builtin_amdgcn_permlane32_swap(__float_as_uint(pmax), __float_as_uint(pmax), false, false);
;     pmax = fmaxf(__uint_as_float(rr[0]), __uint_as_float(rr[1])); }
;   SBAR();
;   PVM(2);
;   if (__builtin_expect(__all(pmax - m_reg <= THR / MLA_SCALE), 1)) { mn = m_reg; alpha = 1.f; }
;   else { mn = fmaxf(m_reg, pmax); alpha = __builtin_amdgcn_exp2f((m_reg - mn) * C); m_reg = mn; }
;   const float mnC = PSHIFT - mn * C;
;   const f32x2 C2 = {C, C}, M2 = {mnC, mnC};
; #pragma unroll
;   for (int r = 0; r < 16; r += 2) { f32x2 v = {p0[r], p0[r + 1]}; v = __builtin_elementwise_fma(v, C2, M2); p0[r] = v[0]; p0[r + 1] = v[1]; }
;   SBAR();
;   PVM(3);
; #pragma unroll
;   for (int r = 0; r < 16; r += 2) { f32x2 v = {p1[r], p1[r + 1]}; v = __builtin_elementwise_fma(v, C2, M2); p1[r] = v[0]; p1[r + 1] = v[1]; }
; #pragma unroll
;   for (int r = 0; r < 8; ++r) p0[r] = __builtin_amdgcn_exp2f(p0[r]);
;   SBAR();
;   lsum = MFMA8(ones8, pa, (f32x16{}));
; #pragma unroll
;   for (int r = 8; r < 16; ++r) p0[r] = __builtin_amdgcn_exp2f(p0[r]);
;   SBAR();
;     ...
; }
.Lu1_dma_done:
	ds_read_b128 v[114:117], v173 offset:29696
	ds_read_b128 v[198:201], v173 offset:30208
	ds_read_b64 v[118:119], v176 offset:28672
	ds_read_b64 v[202:203], v176 offset:28928
	v_exp_f32_e32 v182, v82
	s_waitcnt lgkmcnt(4)
	v_exp_f32_e32 v214, v83
	v_mfma_scale_f32_32x32x64_f8f6f4 v[96:111], v[204:209], v[120:125], 0, v162, v162 op_sel_hi:[0,0,0] cbsz:2 blgp:2
	v_exp_f32_e32 v160, v160
	v_exp_f32_e32 v161, v161
	v_exp_f32_e32 v158, v158
	v_exp_f32_e32 v159, v159
	v_mfma_scale_f32_32x32x64_f8f6f4 v[80:95], v[216:221], v[120:125], 0, v162, v162 op_sel_hi:[0,0,0] cbsz:2 blgp:2
	ds_read_b128 v[66:69], v173 offset:33792
	ds_read_b128 v[72:75], v173 offset:34304
	ds_read_b64 v[70:71], v176 offset:31744
	ds_read_b64 v[76:77], v176 offset:32000
	s_waitcnt lgkmcnt(4)
	v_mfma_scale_f32_32x32x64_f8f6f4 v[96:111], v[114:119], v[126:131], v[96:111], v162, v162 op_sel_hi:[0,0,0] cbsz:2 blgp:2
	v_exp_f32_e32 v113, v156
	v_exp_f32_e32 v114, v157
	v_exp_f32_e32 v115, v154
	v_exp_f32_e32 v116, v155
	v_exp_f32_e32 v117, v152
	v_mfma_scale_f32_32x32x64_f8f6f4 v[80:95], v[198:203], v[126:131], v[80:95], v162, v162 op_sel_hi:[0,0,0] cbsz:2 blgp:2
	v_exp_f32_e32 v118, v153
	s_waitcnt lgkmcnt(0)
	v_exp_f32_e32 v119, v150
	v_mfma_scale_f32_32x32x64_f8f6f4 v[96:111], v[66:71], v[132:137], v[96:111], v162, v162 op_sel_hi:[0,0,0] cbsz:2 blgp:2
	v_exp_f32_e32 v156, v151
	v_exp_f32_e32 v157, v148
	v_exp_f32_e32 v215, v149
	v_mfma_scale_f32_32x32x64_f8f6f4 v[80:95], v[72:77], v[132:137], v[80:95], v162, v162 op_sel_hi:[0,0,0] cbsz:2 blgp:2
	ds_read_b128 v[72:75], v140 offset:20480
	ds_read_b128 v[76:79], v140 offset:20992
	ds_read_b128 v[148:151], v140 offset:22528
	ds_read_b128 v[152:155], v140 offset:23040
	ds_read_b128 v[198:201], v140 offset:24576
	ds_read_b128 v[202:205], v140 offset:25088
	ds_read_b128 v[206:209], v140 offset:26624
	ds_read_b128 v[210:213], v140 offset:27136
	v_cvt_pk_fp8_f32 v64, v65, v197
	v_cvt_pk_fp8_f32 v68, v160, v161
	v_cvt_pk_fp8_f32 v65, v195, v196
	v_cvt_pk_fp8_f32 v69, v182, v214
	v_cvt_pk_fp8_f32 v66, v193, v194
	v_cvt_pk_fp8_f32 v70, v115, v116
	v_cvt_pk_fp8_f32 v67, v188, v190
	v_cvt_pk_fp8_f32 v71, v119, v156
	v_cvt_pk_fp8_f32 v64, v187, v189 op_sel:[0,0,1]
	v_cvt_pk_fp8_f32 v68, v158, v159 op_sel:[0,0,1]
	v_cvt_pk_fp8_f32 v65, v191, v192 op_sel:[0,0,1]
	v_cvt_pk_fp8_f32 v69, v113, v114 op_sel:[0,0,1]
	v_cvt_pk_fp8_f32 v66, v183, v184 op_sel:[0,0,1]
	v_cvt_pk_fp8_f32 v70, v117, v118 op_sel:[0,0,1]
	v_cvt_pk_fp8_f32 v67, v185, v186 op_sel:[0,0,1]
	v_cvt_pk_fp8_f32 v71, v157, v215 op_sel:[0,0,1]
	s_waitcnt lgkmcnt(0)
	s_nop 0
	v_mfma_scale_f32_32x32x64_f8f6f4 v[0:15], v[64:71], v[72:79], v[0:15], v162, v162 op_sel_hi:[0,0,0]
	v_max_f32_e32 v113, v96, v97
	v_max3_f32 v113, v113, v98, v99
	v_max3_f32 v113, v113, v100, v101
	v_max3_f32 v113, v113, v102, v103
	v_max3_f32 v113, v113, v104, v105
	v_max3_f32 v113, v113, v106, v107
	v_max3_f32 v113, v113, v108, v109
	v_max3_f32 v113, v113, v110, v111
	v_mfma_scale_f32_32x32x64_f8f6f4 v[48:63], v[64:71], v[148:155], v[48:63], v162, v162 op_sel_hi:[0,0,0]
	v_max3_f32 v72, v113, v80, v81
	v_max3_f32 v72, v72, v82, v83
	v_max3_f32 v72, v72, v84, v85
	v_max3_f32 v72, v72, v86, v87
	v_max3_f32 v72, v72, v88, v89
	v_max3_f32 v72, v72, v90, v91
	v_max3_f32 v72, v72, v92, v93
	v_max3_f32 v72, v72, v94, v95
	v_mov_b32_e32 v73, v72
	s_nop 1
	v_permlane32_swap_b32_e32 v72, v73
	v_max_f32_e32 v72, v72, v73
	v_mfma_scale_f32_32x32x64_f8f6f4 v[16:31], v[64:71], v[198:205], v[16:31], v162, v162 op_sel_hi:[0,0,0]
	v_sub_f32_e32 v73, v72, v227
	v_cmp_ge_f32_e32 vcc, s69, v73
	s_cmp_eq_u64 vcc, exec
	s_cselect_b64 s[8:9], -1, 0
	v_mov_b32_e32 v182, 1.0
	v_mfma_scale_f32_32x32x64_f8f6f4 v[32:47], v[64:71], v[206:213], v[32:47], v162, v162 op_sel_hi:[0,0,0]
	v_mfma_scale_f32_16x16x128_f8f6f4 v[240:243], v[232:239], v[64:71], 0, v162, v162 op_sel_hi:[0,0,0]
	ds_read_b128 v[200:203], v173 offset:0
	ds_read_b64 v[204:205], v176 offset:0
	ds_read_b128 v[206:209], v173 offset:512
	ds_read_b64 v[210:211], v176 offset:256
	s_and_b64 vcc, exec, s[8:9]
	s_cbranch_vccnz .Lu1_572
	v_max_f32_e32 v148, v227, v72
	v_sub_f32_e32 v72, v227, v148
	v_mul_f32_e32 v72, 0x3dd53b94, v72
	v_exp_f32_e32 v182, v72
	v_mov_b32_e32 v227, v148
	v_fmamk_f32 v230, v148, 0xbdd53b94, v164
	s_and_saveexec_b64 s[16:17], s[6:7]
	ds_write_b32 v178, v182 offset:128
	s_or_b64 exec, exec, s[16:17]
	s_waitcnt lgkmcnt(0)
	v_add_u32_e32 v113, v171, v177
	ds_read_b128 v[72:75], v113 offset:224
	ds_read_b128 v[76:79], v113 offset:192
	ds_read_b128 v[114:117], v113 offset:160
	ds_read_b128 v[150:153], v113 offset:128
	s_waitcnt lgkmcnt(0)
	v_pk_mul_f32 v[12:13], v[12:13], v[72:73]
	v_pk_mul_f32 v[8:9], v[8:9], v[76:77]
	v_pk_mul_f32 v[4:5], v[4:5], v[114:115]
	v_pk_mul_f32 v[14:15], v[14:15], v[74:75]
	v_pk_mul_f32 v[10:11], v[10:11], v[78:79]
	v_pk_mul_f32 v[6:7], v[6:7], v[116:117]
	v_pk_mul_f32 v[2:3], v[2:3], v[152:153]
	v_pk_mul_f32 v[0:1], v[0:1], v[150:151]
	v_pk_mul_f32 v[60:61], v[60:61], v[72:73]
	v_pk_mul_f32 v[56:57], v[56:57], v[76:77]
	v_pk_mul_f32 v[52:53], v[52:53], v[114:115]
	v_pk_mul_f32 v[62:63], v[62:63], v[74:75]
	v_pk_mul_f32 v[58:59], v[58:59], v[78:79]
	v_pk_mul_f32 v[54:55], v[54:55], v[116:117]
	v_pk_mul_f32 v[50:51], v[50:51], v[152:153]
	v_pk_mul_f32 v[48:49], v[48:49], v[150:151]
	v_pk_mul_f32 v[28:29], v[28:29], v[72:73]
	v_pk_mul_f32 v[24:25], v[24:25], v[76:77]
	v_pk_mul_f32 v[20:21], v[20:21], v[114:115]
	v_pk_mul_f32 v[30:31], v[30:31], v[74:75]
	v_pk_mul_f32 v[26:27], v[26:27], v[78:79]
	v_pk_mul_f32 v[22:23], v[22:23], v[116:117]
	v_pk_mul_f32 v[18:19], v[18:19], v[152:153]
	v_pk_mul_f32 v[16:17], v[16:17], v[150:151]
	v_pk_mul_f32 v[44:45], v[44:45], v[72:73]
	v_pk_mul_f32 v[40:41], v[40:41], v[76:77]
	v_pk_mul_f32 v[36:37], v[36:37], v[114:115]
	v_pk_mul_f32 v[46:47], v[46:47], v[74:75]
	v_pk_mul_f32 v[42:43], v[42:43], v[78:79]
	v_pk_mul_f32 v[38:39], v[38:39], v[116:117]
	v_pk_mul_f32 v[34:35], v[34:35], v[152:153]
	v_pk_mul_f32 v[32:33], v[32:33], v[150:151]

; #define SBAR() __builtin_amdgcn_sched_barrier(0)
; #define MFMA8(A, B, C) __builtin_amdgcn_mfma_scale_f32_32x32x64_f8f6f4(A, B, C, 0, 0, 0, 0x7f7f7f7f, 0, 0x7f7f7f7f)
; #define PVM(db) do { const i32x8 b = {(int)f.v[db][0][0], (int)f.v[db][0][1], (int)f.v[db][0][2], (int)f.v[db][0][3], (int)f.v[db][1][0], (int)f.v[db][1][1], (int)f.v[db][1][2], (int)f.v[db][1][3]}; \
;     o[db] = MFMA8(pa, b, o[db]); } while (0)
; DEVINL void pv_psm(f32x16* o, const VFrag& f, const i32x8& pa, f32x16& lsum, const i32x8& ones8,
;                    f32x16& p0, f32x16& p1, float& m_reg, float& mn, float& alpha, int kvalid, int hi) {
;     ...
;   const float mnC = PSHIFT - mn * C;
;   const f32x2 C2 = {C, C}, M2 = {mnC, mnC};
; #pragma unroll
;   for (int r = 0; r < 16; r += 2) { f32x2 v = {p0[r], p0[r + 1]}; v = __builtin_elementwise_fma(v, C2, M2); p0[r] = v[0]; p0[r + 1] = v[1]; }
;   SBAR();
;   PVM(3);
; #pragma unroll
;   for (int r = 0; r < 16; r += 2) { f32x2 v = {p1[r], p1[r + 1]}; v = __builtin_elementwise_fma(v, C2, M2); p1[r] = v[0]; p1[r + 1] = v[1]; }
; #pragma unroll
;   for (int r = 0; r < 8; ++r) p0[r] = __builtin_amdgcn_exp2f(p0[r]);
;   SBAR();
;   lsum = MFMA8(ones8, pa, (f32x16{}));
; #pragma unroll
;   for (int r = 8; r < 16; ++r) p0[r] = __builtin_amdgcn_exp2f(p0[r]);
;   SBAR();
;     ...
; }
.Lu1_576:
	ds_read_b128 v[204:207], v173 offset:9216
	ds_read_b64 v[208:209], v176 offset:9216
	ds_read_b128 v[216:219], v173 offset:9728
	ds_read_b64 v[220:221], v176 offset:9472
	v_pk_fma_f32 v[228:229], v[74:75], s[50:51], v[230:231] op_sel_hi:[1,0,0]
	v_pk_fma_f32 v[66:67], v[66:67], s[50:51], v[230:231] op_sel_hi:[1,0,0]
	v_pk_fma_f32 v[68:69], v[68:69], s[50:51], v[230:231] op_sel_hi:[1,0,0]
	v_pk_fma_f32 v[70:71], v[70:71], s[50:51], v[230:231] op_sel_hi:[1,0,0]
	v_pk_fma_f32 v[72:73], v[72:73], s[50:51], v[230:231] op_sel_hi:[1,0,0]
	v_pk_fma_f32 v[154:155], v[90:91], s[50:51], v[230:231] op_sel_hi:[1,0,0]
	v_pk_fma_f32 v[152:153], v[92:93], s[50:51], v[230:231] op_sel_hi:[1,0,0]
	v_pk_fma_f32 v[150:151], v[94:95], s[50:51], v[230:231] op_sel_hi:[1,0,0]
	v_pk_fma_f32 v[148:149], v[96:97], s[50:51], v[230:231] op_sel_hi:[1,0,0]
	v_exp_f32_e32 v65, v66
	v_exp_f32_e32 v197, v67
	v_exp_f32_e32 v187, v68
	v_exp_f32_e32 v189, v69
	v_exp_f32_e32 v195, v70
	v_exp_f32_e32 v196, v71
	v_exp_f32_e32 v191, v72
	v_exp_f32_e32 v192, v73
	v_fma_f32 v180, v179, v180, v240
	v_mfma_scale_f32_16x16x128_f8f6f4 v[240:243], v[232:239], v[98:105], 0, v162, v162 op_sel_hi:[0,0,0]
	v_fma_f32 v94, v76, s50, v230
	v_fma_f32 v95, v77, s50, v230
	v_fma_f32 v96, v78, s50, v230
	v_fma_f32 v97, v79, s50, v230
	v_fma_f32 v106, v80, s50, v230
	v_fma_f32 v107, v81, s50, v230
	v_exp_f32_e32 v193, v228
	v_exp_f32_e32 v194, v229
	v_exp_f32_e32 v183, v94
	v_exp_f32_e32 v184, v95
	v_exp_f32_e32 v188, v96
	v_exp_f32_e32 v190, v97
	v_exp_f32_e32 v185, v106
	v_exp_f32_e32 v186, v107
	s_add_i32 s53, s53, 2
	v_pk_fma_f32 v[160:161], v[82:83], s[50:51], v[230:231] op_sel_hi:[1,0,0]
	v_pk_fma_f32 v[158:159], v[84:85], s[50:51], v[230:231] op_sel_hi:[1,0,0]
	v_pk_fma_f32 v[82:83], v[86:87], s[50:51], v[230:231] op_sel_hi:[1,0,0]
	v_pk_fma_f32 v[156:157], v[88:89], s[50:51], v[230:231] op_sel_hi:[1,0,0]
	s_cmpk_gt_u32 s53, 0x102
	s_nop 1
	v_fma_f32 v180, v182, v180, v240
	s_cbranch_scc1 .LBB0_578
	v_mov_b32_e32 v179, v198
	s_branch .LBB0_560

; DEVINL int pk8(float a, float b, float c, float d) { int w = 0; w = __builtin_amdgcn_cvt_pk_fp8_f32(a, b, w, false); w = __builtin_amdgcn_cvt_pk_fp8_f32(c, d, w, true); return w; }
; #define SBAR() __builtin_amdgcn_sched_barrier(0)
; #define LSUM() do { lsum = MFMA8(ones8, pa, (f32x16{})); } while (0)
; #define LUPD(al) do { l_reg = l_reg * (al) + lsum[0]; } while (0)
; template <bool EXPDONE>
; DEVINL void finishSM(f32x16& p0, f32x16& p1, float alpha, float& l_reg, i32x8& pa) {
;   if (!EXPDONE) {
; #pragma unroll
;     for (int r = 0; r < 16; ++r) p1[r] = __builtin_amdgcn_exp2f(p1[r]);
;   }
; #pragma unroll
;   for (int i = 0; i < 4; ++i) { pa[i] = pk8(p0[4 * i], p0[4 * i + 1], p0[4 * i + 2], p0[4 * i + 3]); pa[4 + i] = pk8(p1[4 * i], p1[4 * i + 1], p1[4 * i + 2], p1[4 * i + 3]); }
; }
; DEVINL void mla_block(const Params& p, const bf16_t* __restrict__ Qn, const bf16_t* __restrict__ Qr, const char* __restrict__ K8, const char* __restrict__ Kp8,
;                       const char* __restrict__ V8, const bf16_t* __restrict__ Gb, bf16_t* __restrict__ Yb, char* lds, int pos0) {
;     ...
;   pv_load(vf, VS(NT - 1), r32, hi); SBAR();
;   finishSM<false>(pA0, pA1, alA, l_reg, pa); SBAR();
;   pv_mma(o, vf, pa); LSUM(); LUPD(alA);
;   if (hi == 0) li_l[r32] = l_reg; asm volatile("s_waitcnt lgkmcnt(0)" ::: "memory");
.LBB0_578:
	s_setprio 0
	ds_read_b128 v[128:131], v173 offset:36864
	ds_read_b128 v[132:135], v173 offset:37376
	ds_read_b128 v[120:123], v173 offset:38912
	ds_read_b128 v[124:127], v173 offset:39424
	ds_read_b128 v[92:95], v173 offset:40960
	ds_read_b128 v[96:99], v173 offset:41472
	ds_read_b128 v[84:87], v173 offset:43008
	ds_read_b128 v[88:91], v173 offset:43520
	v_exp_f32_e32 v64, v160
	v_exp_f32_e32 v67, v161
	v_exp_f32_e32 v70, v82
	v_exp_f32_e32 v71, v83
	v_exp_f32_e32 v74, v154
	v_exp_f32_e32 v75, v155
	v_exp_f32_e32 v78, v150
	v_exp_f32_e32 v79, v151
	v_mov_b32_e32 v100, v139
	v_mov_b32_e32 v104, v139
	v_mov_b32_e32 v101, v139
	v_mov_b32_e32 v105, v139
	v_mov_b32_e32 v102, v139
	v_mov_b32_e32 v106, v139
	v_mov_b32_e32 v103, v139
	v_mov_b32_e32 v107, v139
	v_exp_f32_e32 v68, v158
	v_exp_f32_e32 v69, v159
	v_exp_f32_e32 v72, v156
	v_exp_f32_e32 v73, v157
	v_exp_f32_e32 v76, v152
	v_exp_f32_e32 v77, v153
	v_exp_f32_e32 v80, v148
	v_exp_f32_e32 v81, v149
	v_cvt_pk_fp8_f32 v100, v65, v197
	v_cvt_pk_fp8_f32 v104, v64, v67
	v_cvt_pk_fp8_f32 v101, v195, v196
	v_cvt_pk_fp8_f32 v105, v70, v71
	v_cvt_pk_fp8_f32 v102, v193, v194
	v_cvt_pk_fp8_f32 v106, v74, v75
	v_cvt_pk_fp8_f32 v103, v188, v190
	v_cvt_pk_fp8_f32 v107, v78, v79
	v_cvt_pk_fp8_f32 v100, v187, v189 op_sel:[0,0,1]
	v_cvt_pk_fp8_f32 v104, v68, v69 op_sel:[0,0,1]
	v_cvt_pk_fp8_f32 v101, v191, v192 op_sel:[0,0,1]
	v_cvt_pk_fp8_f32 v105, v72, v73 op_sel:[0,0,1]
	v_cvt_pk_fp8_f32 v102, v183, v184 op_sel:[0,0,1]
	v_cvt_pk_fp8_f32 v106, v76, v77 op_sel:[0,0,1]
	v_cvt_pk_fp8_f32 v103, v185, v186 op_sel:[0,0,1]
	v_cvt_pk_fp8_f32 v107, v80, v81 op_sel:[0,0,1]
	s_and_saveexec_b64 s[4:5], s[6:7]
	s_cbranch_execz .LBB0_549
	v_mov_b32_e32 v113, v112
	v_mov_b32_e32 v114, v112
	v_mov_b32_e32 v115, v112
	v_mov_b32_e32 v116, v112
	v_mov_b32_e32 v117, v112
	v_mov_b32_e32 v118, v112
	v_mov_b32_e32 v119, v112
	s_nop 1
	v_mfma_scale_f32_16x16x128_f8f6f4 v[68:71], v[232:239], v[100:107], 0, v162, v162 op_sel_hi:[0,0,0]
	s_nop 15
	s_nop 3
	v_fmac_f32_e32 v68, v198, v180
	ds_write_b32 v178, v68
	s_branch .LBB0_549
